# pair GEMM tile order: row groups of 8 panels (a CU keeps its row panel for the whole phase; the epilogue rsqrt cache misses once per phase)
# speedup vs baseline: 1.0120x; 1.0120x over previous
.LBB0_131:
	s_mov_b32 s52, -1
	v_writelane_b32 v248, s52, 41
	s_lshl_b32 s36, s11, 6
	v_mov_b32_e32 v9, v199
	v_readlane_b32 s1, v251, 0
	s_cmp_ge_i32 s1, s36
	v_readfirstlane_b32 s19, v9
	s_mov_b32 s55, s44
	s_cbranch_scc1 .LBB0_151
	v_lshlrev_b32_e32 v0, 4, v9
	s_waitcnt lgkmcnt(0)
	v_add_u32_e32 v1, 0x2000, v0
	v_ashrrev_i32_e32 v2, 31, v1
	v_lshrrev_b32_e32 v2, 22, v2
	v_add_u32_e32 v2, v1, v2
	v_ashrrev_i32_e32 v8, 10, v2
	v_mul_i32_i24_e32 v2, 0x400, v8
	v_sub_u32_e32 v1, v1, v2
	v_lshrrev_b32_e32 v2, 4, v1
	v_bitop3_b32 v1, v2, v1, 32 bitop3:0x6c
	v_ashrrev_i32_e32 v2, 31, v1
	v_lshrrev_b32_e32 v2, 26, v2
	v_add_u32_e32 v2, v1, v2
	v_lshlrev_b32_e32 v3, 3, v8
	v_ashrrev_i32_e32 v10, 6, v2
	v_and_b32_e32 v3, -16, v3
	v_add_u32_e32 v3, v10, v3
	v_and_b32_e32 v4, 3, v10
	s_mov_b32 s2, 0x1fffe0
	v_lshrrev_b32_e32 v5, 2, v3
	v_lshlrev_b32_e32 v6, 1, v3
	v_and_b32_e32 v2, 0xc0, v2
	v_and_or_b32 v4, v3, s2, v4
	v_and_b32_e32 v5, 4, v5
	v_and_b32_e32 v6, 24, v6
	v_sub_u32_e32 v1, v1, v2
	v_or3_b32 v4, v4, v5, v6
	v_lshlrev_b32_e32 v5, 5, v8
	v_ashrrev_i16_sdwa v1, v223, sext(v1) dst_sel:DWORD dst_unused:UNUSED_PAD src0_sel:DWORD src1_sel:BYTE_0
	v_and_b32_e32 v5, 32, v5
	v_bfe_i32 v11, v1, 0, 16
	v_add_lshl_u32 v1, v5, v11, 1
	s_waitcnt vmcnt(0)
	v_lshl_add_u32 v152, v4, 11, v1
	v_lshl_add_u32 v154, v3, 11, v1
	v_bfe_i32 v1, v9, 27, 1
	v_lshrrev_b32_e32 v1, 22, v1
	v_add_u32_e32 v1, v0, v1
	v_and_b32_e32 v1, 0xfffffc00, v1
	v_sub_u32_e32 v0, v0, v1
	v_lshrrev_b32_e32 v1, 4, v0
	v_ashrrev_i32_e32 v2, 31, v9
	v_bitop3_b32 v0, v1, v0, 32 bitop3:0x6c
	v_lshrrev_b32_e32 v2, 26, v2
	v_ashrrev_i32_e32 v1, 31, v0
	v_add_u32_e32 v2, v9, v2
	v_lshrrev_b32_e32 v1, 26, v1
	v_ashrrev_i32_e32 v13, 6, v2
	v_add_u32_e32 v1, v0, v1
	v_lshlrev_b32_e32 v2, 3, v13
	v_ashrrev_i32_e32 v12, 6, v1
	v_and_b32_e32 v2, -16, v2
	v_add_u32_e32 v2, v12, v2
	v_and_b32_e32 v3, 3, v12
	s_ashr_i32 s21, s19, 6
	v_and_or_b32 v3, v2, s2, v3
	s_lshl_b32 s2, s11, 3
	v_readlane_b32 s12, v250, 5
	s_ashr_i32 s20, s19, 8
	s_lshl_b32 s1, s21, 10
	s_or_b32 s3, s2, 1
	v_readlane_b32 s13, v250, 6
	s_and_b64 s[12:13], s[12:13], exec
	v_and_b32_e32 v1, 0xc0, v1
	s_cselect_b32 s12, s3, s2
	s_lshl_b32 s9, s11, 2
	v_sub_u32_e32 v0, v0, v1
	v_cvt_f32_u32_e32 v1, s9
	v_lshrrev_b32_e32 v4, 2, v2
	v_lshlrev_b32_e32 v5, 1, v2
	v_and_b32_e32 v4, 4, v4
	v_and_b32_e32 v5, 24, v5
	v_rcp_iflag_f32_e32 v1, v1
	v_or3_b32 v3, v3, v4, v5
	v_lshlrev_b32_e32 v4, 5, v13
	v_ashrrev_i16_sdwa v0, v223, sext(v0) dst_sel:DWORD dst_unused:UNUSED_PAD src0_sel:DWORD src1_sel:BYTE_0
	v_and_b32_e32 v4, 32, v4
	v_bfe_i32 v14, v0, 0, 16
	v_add_lshl_u32 v0, v4, v14, 1
	v_lshl_add_u32 v196, v3, 11, v0
	v_lshl_add_u32 v156, v2, 11, v0
	v_mul_f32_e32 v0, 0x4f7ffffe, v1
	v_cvt_u32_f32_e32 v0, v0
	v_readlane_b32 s11, v250, 12
	s_mul_i32 s11, s12, s11
	v_readlane_b32 s12, v250, 7
	s_add_i32 s12, s11, s12
	s_sub_i32 s11, 0, s9
	v_readfirstlane_b32 s15, v0
	s_mul_i32 s11, s11, s15
	s_mul_hi_u32 s11, s15, s11
	s_abs_i32 s14, s12
	s_add_i32 s11, s15, s11
	s_mul_hi_u32 s15, s14, s11
	s_mul_i32 s17, s15, s9
	s_sub_i32 s14, s14, s17
	s_ashr_i32 s13, s12, 31
	s_add_i32 s17, s15, 1
	s_sub_i32 s18, s14, s9
	s_cmp_ge_u32 s14, s9
	s_cselect_b32 s15, s17, s15
	s_cselect_b32 s14, s18, s14
	s_add_i32 s17, s15, 1
	s_cmp_ge_u32 s14, s9
	s_cselect_b32 s14, s17, s15
	s_xor_b32 s14, s14, s13
	s_sub_i32 s13, s14, s13
	s_mul_i32 s14, s13, s9
	s_sub_i32 s22, s12, s14
	s_and_b32 s14, s13, 1
	s_mul_i32 s14, s14, s9
	s_add_i32 s22, s22, s14
	s_lshr_b32 s14, s13, 1
	s_lshl_b32 s14, s14, 3
	s_lshr_b32 s18, s22, 3
	s_and_b32 s12, s22, 7
	s_add_i32 s34, s14, s12
	s_ashr_i32 s35, s34, 31
	s_bfe_i64 s[14:15], s[18:19], 0x100000
	s_lshl_b64 s[12:13], s[34:35], 19
	s_lshl_b64 s[14:15], s[14:15], 19
	s_add_u32 s44, s6, s14
	s_addc_u32 s45, s7, s15
	s_add_i32 s14, s1, 0
	s_add_i32 m0, s14, 0x10000
	v_mov_b32_e32 v153, v197
	global_load_lds_dwordx4 v196, s[44:45]
	s_add_i32 m0, s14, 0x12000
	s_add_u32 s22, s44, 0x40000
	global_load_lds_dwordx4 v152, s[44:45]
	s_addc_u32 s23, s45, 0
	s_add_i32 m0, s14, 0x14000
	v_mov_b32_e32 v157, v197
	global_load_lds_dwordx4 v196, s[22:23]
	s_add_i32 m0, s14, 0x16000
	s_add_u32 s40, s80, s12
	s_addc_u32 s41, s81, s13
	s_add_i32 s15, s14, 0x2000
	global_load_lds_dwordx4 v152, s[22:23]
	s_mov_b32 m0, s14
	s_add_u32 s12, s40, 0x40000
	global_load_lds_dwordx4 v156, s[40:41]
	s_mov_b32 m0, s15
	s_addc_u32 s13, s41, 0
	s_add_i32 s17, s14, 0x4000
	global_load_lds_dwordx4 v154, s[40:41]
	s_mov_b32 m0, s17
	s_add_i32 s26, s14, 0x6000
	global_load_lds_dwordx4 v156, s[12:13]
	s_mov_b32 m0, s26
	v_mov_b32_e32 v155, v197
	global_load_lds_dwordx4 v154, s[12:13]
	s_cmp_eq_u32 s20, 1
	s_mov_b32 s56, s30
	v_lshl_add_u64 v[6:7], s[44:45], 0, v[196:197]
	v_lshl_add_u64 v[4:5], s[44:45], 0, v[152:153]
	v_lshl_add_u64 v[0:1], s[40:41], 0, v[156:157]
	s_cselect_b64 s[12:13], -1, 0
	s_cmp_lg_u32 s20, 1
	v_lshl_add_u64 v[2:3], s[40:41], 0, v[154:155]
	s_cbranch_scc1 .LBB0_134
	s_barrier

.LBB0_137:
	v_mov_b32_e32 v228, 0
	v_mov_b32_e32 v229, 0
	v_mov_b32_e32 v230, 0
	v_mov_b32_e32 v231, 0
	v_readlane_b32 s48, v251, 1
	s_add_i32 s29, s29, 1
	v_readlane_b32 s21, v251, 22
	v_readlane_b32 s50, v251, 3
	v_mfma_f32_32x32x16_bf16 v[16:31], v[228:231], v[228:231], 0
	s_mul_i32 s21, s29, s21
	s_mul_hi_u32 s23, s29, s50
	s_add_i32 s23, s23, s21
	s_mul_i32 s21, s29, s50
	v_mfma_f32_32x32x16_bf16 v[32:47], v[228:231], v[228:231], 0
	v_readlane_b32 s24, v251, 0
	s_add_u32 s24, s21, s24
	v_readlane_b32 s21, v251, 21
	s_addc_u32 s25, s23, s21
	v_mfma_f32_32x32x16_bf16 v[48:63], v[228:231], v[228:231], 0
	v_cmp_ge_i64_e32 vcc, s[24:25], v[164:165]
	v_cmp_lt_i64_e64 s[42:43], s[24:25], v[164:165]
	v_readlane_b32 s49, v251, 2
	v_readlane_b32 s51, v251, 4
	v_mfma_f32_32x32x16_bf16 v[64:79], v[228:231], v[228:231], 0
	s_cbranch_vccnz .LBB0_139
	s_ashr_i32 s20, s24, 31
	s_lshr_b32 s20, s20, 29
	s_add_i32 s20, s24, s20
	s_ashr_i32 s21, s20, 3
	s_and_b32 s20, s20, -8
	s_sub_i32 s20, s24, s20
	s_cmp_lt_i32 s20, 0
	s_cselect_b32 s22, s3, s2
	s_mul_i32 s20, s22, s20
	s_add_i32 s20, s20, s21
	s_abs_i32 s22, s20
	s_mul_hi_u32 s23, s22, s11
	s_mul_i32 s24, s23, s9
	s_sub_i32 s22, s22, s24
	s_ashr_i32 s21, s20, 31
	s_add_i32 s24, s23, 1
	s_sub_i32 s25, s22, s9
	s_cmp_ge_u32 s22, s9
	s_cselect_b32 s23, s24, s23
	s_cselect_b32 s22, s25, s22
	s_add_i32 s24, s23, 1
	s_cmp_ge_u32 s22, s9
	s_cselect_b32 s22, s24, s23
	s_xor_b32 s22, s22, s21
	s_sub_i32 s21, s22, s21
	s_mul_i32 s23, s21, s9
	s_sub_i32 s23, s20, s23
	s_and_b32 s24, s21, 1
	s_mul_i32 s24, s24, s9
	s_add_i32 s23, s23, s24
	s_lshr_b32 s22, s21, 1
	s_lshl_b32 s22, s22, 3
	s_lshr_b32 s20, s23, 3
	s_and_b32 s23, s23, 7
	s_add_i32 s22, s22, s23
